# P4/P5 GEMM epilogues: batch the 16 gate/residual loads up front with counted vmcnt waits instead of 16-32 serialized load-wait-store steps
# speedup vs baseline: 1.0139x; 1.0139x over previous
; DI unsigned pk2(float lo, float hi) { f32x2 v = {lo, hi}; bf16v2 r = __builtin_convertvector(v, bf16v2); return __builtin_bit_cast(unsigned, r); }
; DI float bflo(unsigned w) { return __uint_as_float(w << 16); }
; DI float bfhi(unsigned w) { return __uint_as_float(w & 0xffff0000u); }
;     DI void operator()(const f32x4 (&acc)[2][2][4][2], const pg8::Unit& u, int wr, int wc, int fr, int fq) const {
;         const int row0 = u.pm * 256 + wr * 64 + fr, col0 = u.pn * 256 + wc * 32 + 8 * fq;
; #pragma unroll
;         for (int ai = 0; ai < 2; ++ai)
; #pragma unroll
;             for (int m = 0; m < 4; ++m) { const size_t off = (size_t)(row0 + ai * 128 + m * 16) * D + col0;
; #pragma unroll
;                 for (int bj = 0; bj < 2; ++bj) { const f32x4 v0 = acc[ai][bj][m][0], v1 = acc[ai][bj][m][1];
;                     const u32x4 gw = *(const u32x4*)(SMA + off + bj * 128);
;                     u32x4 w; w.x = pk2(v0[0] * bflo(gw.x), v0[1] * bfhi(gw.x)); w.y = pk2(v0[2] * bflo(gw.y), v0[3] * bfhi(gw.y)); w.z = pk2(v1[0] * bflo(gw.z), v1[1] * bfhi(gw.z)); w.w = pk2(v1[2] * bflo(gw.w), v1[3] * bfhi(gw.w));
;                     *(u32x4*)(MG + off + bj * 128) = w; }
;                 asm volatile("" ::: "memory"); }
;     }
.LBB0_110:
	s_cmp_lg_u32 s33, 0
	s_cselect_b64 s[20:21], -1, 0
	v_lshl_add_u32 v160, s36, 8, v166
	v_lshl_or_b32 v162, s35, 8, v168
	v_ashrrev_i32_e32 v161, 31, v160
	v_ashrrev_i32_e32 v163, 31, v162
	s_and_b64 vcc, exec, s[20:21]
	v_or_b32_e32 v134, 16, v160
	v_or_b32_e32 v132, 32, v160
	v_or_b32_e32 v50, 48, v160
	s_cbranch_vccz .LBB0_118
	v_lshlrev_b32_e32 v164, 11, v160
	v_lshl_add_u32 v164, v162, 1, v164
	s_mov_b64 s[2:3], s[78:79]
	global_load_dwordx4 v[178:181], v164, s[2:3]
	global_load_dwordx4 v[182:185], v164, s[2:3] offset:256
	s_add_u32 s2, s2, 0x8000
	s_addc_u32 s3, s3, 0
	global_load_dwordx4 v[186:189], v164, s[2:3]
	global_load_dwordx4 v[190:193], v164, s[2:3] offset:256
	s_add_u32 s2, s2, 0x8000
	s_addc_u32 s3, s3, 0
	global_load_dwordx4 v[194:197], v164, s[2:3]
	global_load_dwordx4 v[198:201], v164, s[2:3] offset:256
	s_add_u32 s2, s2, 0x8000
	s_addc_u32 s3, s3, 0
	global_load_dwordx4 v[202:205], v164, s[2:3]
	global_load_dwordx4 v[206:209], v164, s[2:3] offset:256
	s_add_u32 s2, s2, 0x28000
	s_addc_u32 s3, s3, 0
	global_load_dwordx4 v[210:213], v164, s[2:3]
	global_load_dwordx4 v[214:217], v164, s[2:3] offset:256
	s_add_u32 s2, s2, 0x8000
	s_addc_u32 s3, s3, 0
	global_load_dwordx4 v[218:221], v164, s[2:3]
	global_load_dwordx4 v[222:225], v164, s[2:3] offset:256
	s_add_u32 s2, s2, 0x8000
	s_addc_u32 s3, s3, 0
	global_load_dwordx4 v[226:229], v164, s[2:3]
	global_load_dwordx4 v[230:233], v164, s[2:3] offset:256
	s_add_u32 s2, s2, 0x8000
	s_addc_u32 s3, s3, 0
	global_load_dwordx4 v[132:135], v164, s[2:3]
	global_load_dwordx4 v[160:163], v164, s[2:3] offset:256
	s_mov_b64 s[2:3], s[68:69]
	s_waitcnt vmcnt(15)
	v_lshlrev_b32_e32 v170, 16, v178
	v_and_b32_e32 v171, 0xffff0000, v178
	v_lshlrev_b32_e32 v50, 16, v179
	v_and_b32_e32 v51, 0xffff0000, v179
	v_pk_mul_f32 v[170:171], v[128:129], v[170:171]
	v_pk_mul_f32 v[50:51], v[130:131], v[50:51]
	s_nop 0
	v_cvt_pk_bf16_f32 v178, v170, v171
	v_cvt_pk_bf16_f32 v179, v50, v51
	v_lshlrev_b32_e32 v170, 16, v180
	v_and_b32_e32 v171, 0xffff0000, v180
	v_lshlrev_b32_e32 v50, 16, v181
	v_and_b32_e32 v51, 0xffff0000, v181
	v_pk_mul_f32 v[170:171], v[124:125], v[170:171]
	v_pk_mul_f32 v[50:51], v[126:127], v[50:51]
	s_nop 0
	v_cvt_pk_bf16_f32 v180, v170, v171
	v_cvt_pk_bf16_f32 v181, v50, v51
	global_store_dwordx4 v164, v[178:181], s[2:3]
	s_waitcnt vmcnt(15)
	v_lshlrev_b32_e32 v170, 16, v182
	v_and_b32_e32 v171, 0xffff0000, v182
	v_lshlrev_b32_e32 v50, 16, v183
	v_and_b32_e32 v51, 0xffff0000, v183
	v_pk_mul_f32 v[170:171], v[96:97], v[170:171]
	v_pk_mul_f32 v[50:51], v[98:99], v[50:51]
	s_nop 0
	v_cvt_pk_bf16_f32 v182, v170, v171
	v_cvt_pk_bf16_f32 v183, v50, v51
	v_lshlrev_b32_e32 v170, 16, v184
	v_and_b32_e32 v171, 0xffff0000, v184
	v_lshlrev_b32_e32 v50, 16, v185
	v_and_b32_e32 v51, 0xffff0000, v185
	v_pk_mul_f32 v[170:171], v[92:93], v[170:171]
	v_pk_mul_f32 v[50:51], v[94:95], v[50:51]
	s_nop 0
	v_cvt_pk_bf16_f32 v184, v170, v171
	v_cvt_pk_bf16_f32 v185, v50, v51
	global_store_dwordx4 v164, v[182:185], s[2:3] offset:256
	s_add_u32 s2, s2, 0x8000
	s_addc_u32 s3, s3, 0
	s_waitcnt vmcnt(15)
	v_lshlrev_b32_e32 v170, 16, v186
	v_and_b32_e32 v171, 0xffff0000, v186
	v_lshlrev_b32_e32 v50, 16, v187
	v_and_b32_e32 v51, 0xffff0000, v187
	v_pk_mul_f32 v[170:171], v[120:121], v[170:171]
	v_pk_mul_f32 v[50:51], v[122:123], v[50:51]
	s_nop 0
	v_cvt_pk_bf16_f32 v186, v170, v171
	v_cvt_pk_bf16_f32 v187, v50, v51
	v_lshlrev_b32_e32 v170, 16, v188
	v_and_b32_e32 v171, 0xffff0000, v188
	v_lshlrev_b32_e32 v50, 16, v189
	v_and_b32_e32 v51, 0xffff0000, v189
	v_pk_mul_f32 v[170:171], v[116:117], v[170:171]
	v_pk_mul_f32 v[50:51], v[118:119], v[50:51]
	s_nop 0
	v_cvt_pk_bf16_f32 v188, v170, v171
	v_cvt_pk_bf16_f32 v189, v50, v51
	global_store_dwordx4 v164, v[186:189], s[2:3]
	s_waitcnt vmcnt(15)
	v_lshlrev_b32_e32 v170, 16, v190
	v_and_b32_e32 v171, 0xffff0000, v190
	v_lshlrev_b32_e32 v50, 16, v191
	v_and_b32_e32 v51, 0xffff0000, v191
	v_pk_mul_f32 v[170:171], v[88:89], v[170:171]
	v_pk_mul_f32 v[50:51], v[90:91], v[50:51]
	s_nop 0
	v_cvt_pk_bf16_f32 v190, v170, v171
	v_cvt_pk_bf16_f32 v191, v50, v51
	v_lshlrev_b32_e32 v170, 16, v192
	v_and_b32_e32 v171, 0xffff0000, v192
	v_lshlrev_b32_e32 v50, 16, v193
	v_and_b32_e32 v51, 0xffff0000, v193
	v_pk_mul_f32 v[170:171], v[84:85], v[170:171]
	v_pk_mul_f32 v[50:51], v[86:87], v[50:51]
	s_nop 0
	v_cvt_pk_bf16_f32 v192, v170, v171
	v_cvt_pk_bf16_f32 v193, v50, v51
	global_store_dwordx4 v164, v[190:193], s[2:3] offset:256
	s_add_u32 s2, s2, 0x8000
	s_addc_u32 s3, s3, 0
	s_waitcnt vmcnt(15)
	v_lshlrev_b32_e32 v170, 16, v194
	v_and_b32_e32 v171, 0xffff0000, v194
	v_lshlrev_b32_e32 v50, 16, v195
	v_and_b32_e32 v51, 0xffff0000, v195
	v_pk_mul_f32 v[170:171], v[112:113], v[170:171]
	v_pk_mul_f32 v[50:51], v[114:115], v[50:51]
	s_nop 0
	v_cvt_pk_bf16_f32 v194, v170, v171
	v_cvt_pk_bf16_f32 v195, v50, v51
	v_lshlrev_b32_e32 v170, 16, v196
	v_and_b32_e32 v171, 0xffff0000, v196
	v_lshlrev_b32_e32 v50, 16, v197
	v_and_b32_e32 v51, 0xffff0000, v197
	v_pk_mul_f32 v[170:171], v[108:109], v[170:171]
	v_pk_mul_f32 v[50:51], v[110:111], v[50:51]
	s_nop 0
	v_cvt_pk_bf16_f32 v196, v170, v171
	v_cvt_pk_bf16_f32 v197, v50, v51
	global_store_dwordx4 v164, v[194:197], s[2:3]
	s_waitcnt vmcnt(15)
	v_lshlrev_b32_e32 v170, 16, v198
	v_and_b32_e32 v171, 0xffff0000, v198
	v_lshlrev_b32_e32 v50, 16, v199
	v_and_b32_e32 v51, 0xffff0000, v199
	v_pk_mul_f32 v[170:171], v[80:81], v[170:171]
	v_pk_mul_f32 v[50:51], v[82:83], v[50:51]
	s_nop 0
	v_cvt_pk_bf16_f32 v198, v170, v171
	v_cvt_pk_bf16_f32 v199, v50, v51
	v_lshlrev_b32_e32 v170, 16, v200
	v_and_b32_e32 v171, 0xffff0000, v200
	v_lshlrev_b32_e32 v50, 16, v201
	v_and_b32_e32 v51, 0xffff0000, v201
	v_pk_mul_f32 v[170:171], v[76:77], v[170:171]
	v_pk_mul_f32 v[50:51], v[78:79], v[50:51]
	s_nop 0
	v_cvt_pk_bf16_f32 v200, v170, v171
	v_cvt_pk_bf16_f32 v201, v50, v51
	global_store_dwordx4 v164, v[198:201], s[2:3] offset:256
	s_add_u32 s2, s2, 0x8000
	s_addc_u32 s3, s3, 0
	s_waitcnt vmcnt(15)
; DI unsigned pk2(float lo, float hi) { f32x2 v = {lo, hi}; bf16v2 r = __builtin_convertvector(v, bf16v2); return __builtin_bit_cast(unsigned, r); }
; DI float bflo(unsigned w) { return __uint_as_float(w << 16); }
; DI float bfhi(unsigned w) { return __uint_as_float(w & 0xffff0000u); }
;     DI void operator()(const f32x4 (&acc)[2][2][4][2], const pg8::Unit& u, int wr, int wc, int fr, int fq) const {
;     ...
;                 for (int bj = 0; bj < 2; ++bj) { const f32x4 v0 = acc[ai][bj][m][0], v1 = acc[ai][bj][m][1];
;                     const u32x4 gw = *(const u32x4*)(SMA + off + bj * 128);
;                     u32x4 w; w.x = pk2(v0[0] * bflo(gw.x), v0[1] * bfhi(gw.x)); w.y = pk2(v0[2] * bflo(gw.y), v0[3] * bfhi(gw.y)); w.z = pk2(v1[0] * bflo(gw.z), v1[1] * bfhi(gw.z)); w.w = pk2(v1[2] * bflo(gw.w), v1[3] * bfhi(gw.w));
;                     *(u32x4*)(MG + off + bj * 128) = w; }
	v_lshlrev_b32_e32 v170, 16, v202
	v_and_b32_e32 v171, 0xffff0000, v202
	v_lshlrev_b32_e32 v50, 16, v203
	v_and_b32_e32 v51, 0xffff0000, v203
	v_pk_mul_f32 v[170:171], v[104:105], v[170:171]
	v_pk_mul_f32 v[50:51], v[106:107], v[50:51]
	s_nop 0
	v_cvt_pk_bf16_f32 v202, v170, v171
	v_cvt_pk_bf16_f32 v203, v50, v51
	v_lshlrev_b32_e32 v170, 16, v204
	v_and_b32_e32 v171, 0xffff0000, v204
	v_lshlrev_b32_e32 v50, 16, v205
	v_and_b32_e32 v51, 0xffff0000, v205
	v_pk_mul_f32 v[170:171], v[100:101], v[170:171]
	v_pk_mul_f32 v[50:51], v[102:103], v[50:51]
	s_nop 0
	v_cvt_pk_bf16_f32 v204, v170, v171
	v_cvt_pk_bf16_f32 v205, v50, v51
	global_store_dwordx4 v164, v[202:205], s[2:3]
	s_waitcnt vmcnt(15)
	v_lshlrev_b32_e32 v170, 16, v206
	v_and_b32_e32 v171, 0xffff0000, v206
	v_lshlrev_b32_e32 v50, 16, v207
	v_and_b32_e32 v51, 0xffff0000, v207
	v_pk_mul_f32 v[170:171], v[72:73], v[170:171]
	v_pk_mul_f32 v[50:51], v[74:75], v[50:51]
	s_nop 0
	v_cvt_pk_bf16_f32 v206, v170, v171
	v_cvt_pk_bf16_f32 v207, v50, v51
	v_lshlrev_b32_e32 v170, 16, v208
	v_and_b32_e32 v171, 0xffff0000, v208
	v_lshlrev_b32_e32 v50, 16, v209
	v_and_b32_e32 v51, 0xffff0000, v209
	v_pk_mul_f32 v[170:171], v[68:69], v[170:171]
	v_pk_mul_f32 v[50:51], v[70:71], v[50:51]
	s_nop 0
	v_cvt_pk_bf16_f32 v208, v170, v171
	v_cvt_pk_bf16_f32 v209, v50, v51
	global_store_dwordx4 v164, v[206:209], s[2:3] offset:256
	s_add_u32 s2, s2, 0x28000
	s_addc_u32 s3, s3, 0
	s_waitcnt vmcnt(15)
	v_lshlrev_b32_e32 v170, 16, v210
	v_and_b32_e32 v171, 0xffff0000, v210
	v_lshlrev_b32_e32 v50, 16, v211
	v_and_b32_e32 v51, 0xffff0000, v211
	v_pk_mul_f32 v[170:171], v[64:65], v[170:171]
	v_pk_mul_f32 v[50:51], v[66:67], v[50:51]
	s_nop 0
	v_cvt_pk_bf16_f32 v210, v170, v171
	v_cvt_pk_bf16_f32 v211, v50, v51
	v_lshlrev_b32_e32 v170, 16, v212
	v_and_b32_e32 v171, 0xffff0000, v212
	v_lshlrev_b32_e32 v50, 16, v213
	v_and_b32_e32 v51, 0xffff0000, v213
	v_pk_mul_f32 v[170:171], v[60:61], v[170:171]
	v_pk_mul_f32 v[50:51], v[62:63], v[50:51]
	s_nop 0
	v_cvt_pk_bf16_f32 v212, v170, v171
	v_cvt_pk_bf16_f32 v213, v50, v51
	global_store_dwordx4 v164, v[210:213], s[2:3]
	s_waitcnt vmcnt(15)
	v_lshlrev_b32_e32 v170, 16, v214
	v_and_b32_e32 v171, 0xffff0000, v214
	v_lshlrev_b32_e32 v50, 16, v215
	v_and_b32_e32 v51, 0xffff0000, v215
	v_pk_mul_f32 v[170:171], v[28:29], v[170:171]
	v_pk_mul_f32 v[50:51], v[30:31], v[50:51]
	s_nop 0
	v_cvt_pk_bf16_f32 v214, v170, v171
	v_cvt_pk_bf16_f32 v215, v50, v51
	v_lshlrev_b32_e32 v170, 16, v216
	v_and_b32_e32 v171, 0xffff0000, v216
	v_lshlrev_b32_e32 v50, 16, v217
	v_and_b32_e32 v51, 0xffff0000, v217
	v_pk_mul_f32 v[170:171], v[24:25], v[170:171]
	v_pk_mul_f32 v[50:51], v[26:27], v[50:51]
	s_nop 0
	v_cvt_pk_bf16_f32 v216, v170, v171
	v_cvt_pk_bf16_f32 v217, v50, v51
	global_store_dwordx4 v164, v[214:217], s[2:3] offset:256
	s_add_u32 s2, s2, 0x8000
	s_addc_u32 s3, s3, 0
	s_waitcnt vmcnt(15)
	v_lshlrev_b32_e32 v170, 16, v218
	v_and_b32_e32 v171, 0xffff0000, v218
	v_lshlrev_b32_e32 v50, 16, v219
	v_and_b32_e32 v51, 0xffff0000, v219
	v_pk_mul_f32 v[170:171], v[56:57], v[170:171]
	v_pk_mul_f32 v[50:51], v[58:59], v[50:51]
	s_nop 0
	v_cvt_pk_bf16_f32 v218, v170, v171
	v_cvt_pk_bf16_f32 v219, v50, v51
	v_lshlrev_b32_e32 v170, 16, v220
	v_and_b32_e32 v171, 0xffff0000, v220
	v_lshlrev_b32_e32 v50, 16, v221
	v_and_b32_e32 v51, 0xffff0000, v221
	v_pk_mul_f32 v[170:171], v[52:53], v[170:171]
	v_pk_mul_f32 v[50:51], v[54:55], v[50:51]
	s_nop 0
	v_cvt_pk_bf16_f32 v220, v170, v171
	v_cvt_pk_bf16_f32 v221, v50, v51
	global_store_dwordx4 v164, v[218:221], s[2:3]
	s_waitcnt vmcnt(15)
	v_lshlrev_b32_e32 v170, 16, v222
	v_and_b32_e32 v171, 0xffff0000, v222
	v_lshlrev_b32_e32 v50, 16, v223
	v_and_b32_e32 v51, 0xffff0000, v223
	v_pk_mul_f32 v[170:171], v[20:21], v[170:171]
	v_pk_mul_f32 v[50:51], v[22:23], v[50:51]
	s_nop 0
	v_cvt_pk_bf16_f32 v222, v170, v171
	v_cvt_pk_bf16_f32 v223, v50, v51
	v_lshlrev_b32_e32 v170, 16, v224
	v_and_b32_e32 v171, 0xffff0000, v224
	v_lshlrev_b32_e32 v50, 16, v225
	v_and_b32_e32 v51, 0xffff0000, v225
	v_pk_mul_f32 v[170:171], v[16:17], v[170:171]
	v_pk_mul_f32 v[50:51], v[18:19], v[50:51]
	s_nop 0
	v_cvt_pk_bf16_f32 v224, v170, v171
	v_cvt_pk_bf16_f32 v225, v50, v51
	global_store_dwordx4 v164, v[222:225], s[2:3] offset:256
	s_add_u32 s2, s2, 0x8000
	s_addc_u32 s3, s3, 0
	s_waitcnt vmcnt(15)
	v_lshlrev_b32_e32 v170, 16, v226
	v_and_b32_e32 v171, 0xffff0000, v226
	v_lshlrev_b32_e32 v50, 16, v227
	v_and_b32_e32 v51, 0xffff0000, v227
	v_pk_mul_f32 v[170:171], v[44:45], v[170:171]
	v_pk_mul_f32 v[50:51], v[46:47], v[50:51]
	s_nop 0
	v_cvt_pk_bf16_f32 v226, v170, v171
	v_cvt_pk_bf16_f32 v227, v50, v51
	v_lshlrev_b32_e32 v170, 16, v228
	v_and_b32_e32 v171, 0xffff0000, v228
	v_lshlrev_b32_e32 v50, 16, v229
	v_and_b32_e32 v51, 0xffff0000, v229
	v_pk_mul_f32 v[170:171], v[40:41], v[170:171]
	v_pk_mul_f32 v[50:51], v[42:43], v[50:51]
	s_nop 0
	v_cvt_pk_bf16_f32 v228, v170, v171
	v_cvt_pk_bf16_f32 v229, v50, v51
	global_store_dwordx4 v164, v[226:229], s[2:3]
	s_waitcnt vmcnt(15)
	v_lshlrev_b32_e32 v170, 16, v230
	v_and_b32_e32 v171, 0xffff0000, v230
	v_lshlrev_b32_e32 v50, 16, v231
	v_and_b32_e32 v51, 0xffff0000, v231
	v_pk_mul_f32 v[170:171], v[12:13], v[170:171]
	v_pk_mul_f32 v[50:51], v[14:15], v[50:51]
	s_nop 0
	v_cvt_pk_bf16_f32 v230, v170, v171
	v_cvt_pk_bf16_f32 v231, v50, v51
	v_lshlrev_b32_e32 v170, 16, v232
	v_and_b32_e32 v171, 0xffff0000, v232
	v_lshlrev_b32_e32 v50, 16, v233
	v_and_b32_e32 v51, 0xffff0000, v233
	v_pk_mul_f32 v[170:171], v[8:9], v[170:171]
	v_pk_mul_f32 v[50:51], v[10:11], v[50:51]
	s_nop 0
	v_cvt_pk_bf16_f32 v232, v170, v171
	v_cvt_pk_bf16_f32 v233, v50, v51
	global_store_dwordx4 v164, v[230:233], s[2:3] offset:256
	s_add_u32 s2, s2, 0x8000
	s_addc_u32 s3, s3, 0
	s_waitcnt vmcnt(15)
; DI unsigned pk2(float lo, float hi) { f32x2 v = {lo, hi}; bf16v2 r = __builtin_convertvector(v, bf16v2); return __builtin_bit_cast(unsigned, r); }
; DI float bflo(unsigned w) { return __uint_as_float(w << 16); }
; DI float bfhi(unsigned w) { return __uint_as_float(w & 0xffff0000u); }
;     DI void mid(f32x4 (&acc)[2][2][4][2], const pg8::Unit& u, int wr, int wc, int fr, int fq) const {
;     ...
;             for (int m = 0; m < 4; ++m) { const size_t off = (size_t)(row0 + ai * 128 + m * 16) * D + col0;
; #pragma unroll
;                 for (int bj = 0; bj < 2; ++bj) { const u32x4 gw = *(const u32x4*)(RHO + off + bj * 128);
;                     acc[ai][bj][m][0] = acc[ai][bj][m][0] * (f32x4){bflo(gw.x), bfhi(gw.x), bflo(gw.y), bfhi(gw.y)};
;                     acc[ai][bj][m][1] = acc[ai][bj][m][1] * (f32x4){bflo(gw.z), bfhi(gw.z), bflo(gw.w), bfhi(gw.w)}; }
;     DI void operator()(const f32x4 (&acc)[2][2][4][2], const pg8::Unit& u, int wr, int wc, int fr, int fq) const {
;     ...
;                 for (int bj = 0; bj < 2; ++bj) { const f32x4 v0 = acc[ai][bj][m][0], v1 = acc[ai][bj][m][1];
;                     const u32x4 gw = *(const u32x4*)(SMA + off + bj * 128);
;                     u32x4 w; w.x = pk2(v0[0] * bflo(gw.x), v0[1] * bfhi(gw.x)); w.y = pk2(v0[2] * bflo(gw.y), v0[3] * bfhi(gw.y)); w.z = pk2(v1[0] * bflo(gw.z), v1[1] * bfhi(gw.z)); w.w = pk2(v1[2] * bflo(gw.w), v1[3] * bfhi(gw.w));
;                     *(u32x4*)(MG + off + bj * 128) = w; }
	v_lshlrev_b32_e32 v170, 16, v132
	v_and_b32_e32 v171, 0xffff0000, v132
	v_lshlrev_b32_e32 v50, 16, v133
	v_and_b32_e32 v51, 0xffff0000, v133
	v_pk_mul_f32 v[170:171], v[36:37], v[170:171]
	v_pk_mul_f32 v[50:51], v[38:39], v[50:51]
	s_nop 0
	v_cvt_pk_bf16_f32 v132, v170, v171
	v_cvt_pk_bf16_f32 v133, v50, v51
	v_lshlrev_b32_e32 v170, 16, v134
	v_and_b32_e32 v171, 0xffff0000, v134
	v_lshlrev_b32_e32 v50, 16, v135
	v_and_b32_e32 v51, 0xffff0000, v135
	v_pk_mul_f32 v[170:171], v[32:33], v[170:171]
	v_pk_mul_f32 v[50:51], v[34:35], v[50:51]
	s_nop 0
	v_cvt_pk_bf16_f32 v134, v170, v171
	v_cvt_pk_bf16_f32 v135, v50, v51
	global_store_dwordx4 v164, v[132:135], s[2:3]
	s_waitcnt vmcnt(15)
	v_lshlrev_b32_e32 v170, 16, v160
	v_and_b32_e32 v171, 0xffff0000, v160
	v_lshlrev_b32_e32 v50, 16, v161
	v_and_b32_e32 v51, 0xffff0000, v161
	v_pk_mul_f32 v[170:171], v[4:5], v[170:171]
	v_pk_mul_f32 v[50:51], v[6:7], v[50:51]
	s_nop 0
	v_cvt_pk_bf16_f32 v160, v170, v171
	v_cvt_pk_bf16_f32 v161, v50, v51
	v_lshlrev_b32_e32 v170, 16, v162
	v_and_b32_e32 v171, 0xffff0000, v162
	v_lshlrev_b32_e32 v50, 16, v163
	v_and_b32_e32 v51, 0xffff0000, v163
	v_pk_mul_f32 v[170:171], v[0:1], v[170:171]
	v_pk_mul_f32 v[50:51], v[2:3], v[50:51]
	s_nop 0
	v_cvt_pk_bf16_f32 v162, v170, v171
	v_cvt_pk_bf16_f32 v163, v50, v51
	global_store_dwordx4 v164, v[160:163], s[2:3] offset:256
	s_cbranch_execnz .LBB0_113
.LBB0_112:
	v_lshlrev_b32_e32 v164, 11, v160
	v_lshl_add_u32 v164, v162, 1, v164
	s_mov_b64 s[2:3], s[80:81]
	global_load_dwordx4 v[178:181], v164, s[2:3]
	global_load_dwordx4 v[182:185], v164, s[2:3] offset:256
	s_add_u32 s2, s2, 0x8000
	s_addc_u32 s3, s3, 0
	global_load_dwordx4 v[186:189], v164, s[2:3]
	global_load_dwordx4 v[190:193], v164, s[2:3] offset:256
	s_add_u32 s2, s2, 0x8000
	s_addc_u32 s3, s3, 0
	global_load_dwordx4 v[194:197], v164, s[2:3]
	global_load_dwordx4 v[198:201], v164, s[2:3] offset:256
	s_add_u32 s2, s2, 0x8000
	s_addc_u32 s3, s3, 0
	global_load_dwordx4 v[202:205], v164, s[2:3]
	global_load_dwordx4 v[206:209], v164, s[2:3] offset:256
	s_add_u32 s2, s2, 0x28000
	s_addc_u32 s3, s3, 0
	global_load_dwordx4 v[210:213], v164, s[2:3]
	global_load_dwordx4 v[214:217], v164, s[2:3] offset:256
	s_add_u32 s2, s2, 0x8000
	s_addc_u32 s3, s3, 0
	global_load_dwordx4 v[218:221], v164, s[2:3]
	global_load_dwordx4 v[222:225], v164, s[2:3] offset:256
	s_add_u32 s2, s2, 0x8000
	s_addc_u32 s3, s3, 0
	global_load_dwordx4 v[226:229], v164, s[2:3]
	global_load_dwordx4 v[230:233], v164, s[2:3] offset:256
	s_add_u32 s2, s2, 0x8000
	s_addc_u32 s3, s3, 0
	global_load_dwordx4 v[132:135], v164, s[2:3]
	global_load_dwordx4 v[160:163], v164, s[2:3] offset:256
	s_waitcnt vmcnt(15)
	v_lshlrev_b32_e32 v170, 16, v178
	v_and_b32_e32 v171, 0xffff0000, v178
	v_lshlrev_b32_e32 v50, 16, v179
	v_and_b32_e32 v51, 0xffff0000, v179
	v_pk_mul_f32 v[128:129], v[128:129], v[170:171]
	v_pk_mul_f32 v[130:131], v[130:131], v[50:51]
	v_lshlrev_b32_e32 v170, 16, v180
	v_and_b32_e32 v171, 0xffff0000, v180
	v_lshlrev_b32_e32 v50, 16, v181
	v_and_b32_e32 v51, 0xffff0000, v181
	v_pk_mul_f32 v[124:125], v[124:125], v[170:171]
	v_pk_mul_f32 v[126:127], v[126:127], v[50:51]
	s_waitcnt vmcnt(14)
	v_lshlrev_b32_e32 v170, 16, v182
	v_and_b32_e32 v171, 0xffff0000, v182
	v_lshlrev_b32_e32 v50, 16, v183
	v_and_b32_e32 v51, 0xffff0000, v183
	v_pk_mul_f32 v[96:97], v[96:97], v[170:171]
	v_pk_mul_f32 v[98:99], v[98:99], v[50:51]
	v_lshlrev_b32_e32 v170, 16, v184
	v_and_b32_e32 v171, 0xffff0000, v184
	v_lshlrev_b32_e32 v50, 16, v185
	v_and_b32_e32 v51, 0xffff0000, v185
	v_pk_mul_f32 v[92:93], v[92:93], v[170:171]
	v_pk_mul_f32 v[94:95], v[94:95], v[50:51]
	s_waitcnt vmcnt(13)
	v_lshlrev_b32_e32 v170, 16, v186
	v_and_b32_e32 v171, 0xffff0000, v186
	v_lshlrev_b32_e32 v50, 16, v187
	v_and_b32_e32 v51, 0xffff0000, v187
	v_pk_mul_f32 v[120:121], v[120:121], v[170:171]
	v_pk_mul_f32 v[122:123], v[122:123], v[50:51]
	v_lshlrev_b32_e32 v170, 16, v188
	v_and_b32_e32 v171, 0xffff0000, v188
	v_lshlrev_b32_e32 v50, 16, v189
	v_and_b32_e32 v51, 0xffff0000, v189
	v_pk_mul_f32 v[116:117], v[116:117], v[170:171]
	v_pk_mul_f32 v[118:119], v[118:119], v[50:51]
	s_waitcnt vmcnt(12)
	v_lshlrev_b32_e32 v170, 16, v190
	v_and_b32_e32 v171, 0xffff0000, v190
	v_lshlrev_b32_e32 v50, 16, v191
	v_and_b32_e32 v51, 0xffff0000, v191
	v_pk_mul_f32 v[88:89], v[88:89], v[170:171]
	v_pk_mul_f32 v[90:91], v[90:91], v[50:51]
	v_lshlrev_b32_e32 v170, 16, v192
	v_and_b32_e32 v171, 0xffff0000, v192
	v_lshlrev_b32_e32 v50, 16, v193
	v_and_b32_e32 v51, 0xffff0000, v193
	v_pk_mul_f32 v[84:85], v[84:85], v[170:171]
	v_pk_mul_f32 v[86:87], v[86:87], v[50:51]
	s_waitcnt vmcnt(11)
	v_lshlrev_b32_e32 v170, 16, v194
	v_and_b32_e32 v171, 0xffff0000, v194
	v_lshlrev_b32_e32 v50, 16, v195
	v_and_b32_e32 v51, 0xffff0000, v195
	v_pk_mul_f32 v[112:113], v[112:113], v[170:171]
	v_pk_mul_f32 v[114:115], v[114:115], v[50:51]
	v_lshlrev_b32_e32 v170, 16, v196
	v_and_b32_e32 v171, 0xffff0000, v196
	v_lshlrev_b32_e32 v50, 16, v197
	v_and_b32_e32 v51, 0xffff0000, v197
	v_pk_mul_f32 v[108:109], v[108:109], v[170:171]
	v_pk_mul_f32 v[110:111], v[110:111], v[50:51]
	s_waitcnt vmcnt(10)
; DI float bflo(unsigned w) { return __uint_as_float(w << 16); }
; DI float bfhi(unsigned w) { return __uint_as_float(w & 0xffff0000u); }
;     DI void mid(f32x4 (&acc)[2][2][4][2], const pg8::Unit& u, int wr, int wc, int fr, int fq) const {
;     ...
;             for (int m = 0; m < 4; ++m) { const size_t off = (size_t)(row0 + ai * 128 + m * 16) * D + col0;
; #pragma unroll
;                 for (int bj = 0; bj < 2; ++bj) { const u32x4 gw = *(const u32x4*)(RHO + off + bj * 128);
;                     acc[ai][bj][m][0] = acc[ai][bj][m][0] * (f32x4){bflo(gw.x), bfhi(gw.x), bflo(gw.y), bfhi(gw.y)};
;                     acc[ai][bj][m][1] = acc[ai][bj][m][1] * (f32x4){bflo(gw.z), bfhi(gw.z), bflo(gw.w), bfhi(gw.w)}; }
	v_lshlrev_b32_e32 v170, 16, v198
	v_and_b32_e32 v171, 0xffff0000, v198
	v_lshlrev_b32_e32 v50, 16, v199
	v_and_b32_e32 v51, 0xffff0000, v199
	v_pk_mul_f32 v[80:81], v[80:81], v[170:171]
	v_pk_mul_f32 v[82:83], v[82:83], v[50:51]
	v_lshlrev_b32_e32 v170, 16, v200
	v_and_b32_e32 v171, 0xffff0000, v200
	v_lshlrev_b32_e32 v50, 16, v201
	v_and_b32_e32 v51, 0xffff0000, v201
	v_pk_mul_f32 v[76:77], v[76:77], v[170:171]
	v_pk_mul_f32 v[78:79], v[78:79], v[50:51]
	s_waitcnt vmcnt(9)
	v_lshlrev_b32_e32 v170, 16, v202
	v_and_b32_e32 v171, 0xffff0000, v202
	v_lshlrev_b32_e32 v50, 16, v203
	v_and_b32_e32 v51, 0xffff0000, v203
	v_pk_mul_f32 v[104:105], v[104:105], v[170:171]
	v_pk_mul_f32 v[106:107], v[106:107], v[50:51]
	v_lshlrev_b32_e32 v170, 16, v204
	v_and_b32_e32 v171, 0xffff0000, v204
	v_lshlrev_b32_e32 v50, 16, v205
	v_and_b32_e32 v51, 0xffff0000, v205
	v_pk_mul_f32 v[100:101], v[100:101], v[170:171]
	v_pk_mul_f32 v[102:103], v[102:103], v[50:51]
	s_waitcnt vmcnt(8)
	v_lshlrev_b32_e32 v170, 16, v206
	v_and_b32_e32 v171, 0xffff0000, v206
	v_lshlrev_b32_e32 v50, 16, v207
	v_and_b32_e32 v51, 0xffff0000, v207
	v_pk_mul_f32 v[72:73], v[72:73], v[170:171]
	v_pk_mul_f32 v[74:75], v[74:75], v[50:51]
	v_lshlrev_b32_e32 v170, 16, v208
	v_and_b32_e32 v171, 0xffff0000, v208
	v_lshlrev_b32_e32 v50, 16, v209
	v_and_b32_e32 v51, 0xffff0000, v209
	v_pk_mul_f32 v[68:69], v[68:69], v[170:171]
	v_pk_mul_f32 v[70:71], v[70:71], v[50:51]
	s_waitcnt vmcnt(7)
	v_lshlrev_b32_e32 v170, 16, v210
	v_and_b32_e32 v171, 0xffff0000, v210
	v_lshlrev_b32_e32 v50, 16, v211
	v_and_b32_e32 v51, 0xffff0000, v211
	v_pk_mul_f32 v[64:65], v[64:65], v[170:171]
	v_pk_mul_f32 v[66:67], v[66:67], v[50:51]
	v_lshlrev_b32_e32 v170, 16, v212
	v_and_b32_e32 v171, 0xffff0000, v212
	v_lshlrev_b32_e32 v50, 16, v213
	v_and_b32_e32 v51, 0xffff0000, v213
	v_pk_mul_f32 v[60:61], v[60:61], v[170:171]
	v_pk_mul_f32 v[62:63], v[62:63], v[50:51]
	s_waitcnt vmcnt(6)
	v_lshlrev_b32_e32 v170, 16, v214
	v_and_b32_e32 v171, 0xffff0000, v214
	v_lshlrev_b32_e32 v50, 16, v215
	v_and_b32_e32 v51, 0xffff0000, v215
	v_pk_mul_f32 v[28:29], v[28:29], v[170:171]
	v_pk_mul_f32 v[30:31], v[30:31], v[50:51]
	v_lshlrev_b32_e32 v170, 16, v216
	v_and_b32_e32 v171, 0xffff0000, v216
	v_lshlrev_b32_e32 v50, 16, v217
	v_and_b32_e32 v51, 0xffff0000, v217
	v_pk_mul_f32 v[24:25], v[24:25], v[170:171]
	v_pk_mul_f32 v[26:27], v[26:27], v[50:51]
	s_waitcnt vmcnt(5)
	v_lshlrev_b32_e32 v170, 16, v218
	v_and_b32_e32 v171, 0xffff0000, v218
	v_lshlrev_b32_e32 v50, 16, v219
	v_and_b32_e32 v51, 0xffff0000, v219
	v_pk_mul_f32 v[56:57], v[56:57], v[170:171]
	v_pk_mul_f32 v[58:59], v[58:59], v[50:51]
	v_lshlrev_b32_e32 v170, 16, v220
	v_and_b32_e32 v171, 0xffff0000, v220
	v_lshlrev_b32_e32 v50, 16, v221
	v_and_b32_e32 v51, 0xffff0000, v221
	v_pk_mul_f32 v[52:53], v[52:53], v[170:171]
	v_pk_mul_f32 v[54:55], v[54:55], v[50:51]
	s_waitcnt vmcnt(4)
	v_lshlrev_b32_e32 v170, 16, v222
	v_and_b32_e32 v171, 0xffff0000, v222
	v_lshlrev_b32_e32 v50, 16, v223
	v_and_b32_e32 v51, 0xffff0000, v223
	v_pk_mul_f32 v[20:21], v[20:21], v[170:171]
	v_pk_mul_f32 v[22:23], v[22:23], v[50:51]
	v_lshlrev_b32_e32 v170, 16, v224
	v_and_b32_e32 v171, 0xffff0000, v224
	v_lshlrev_b32_e32 v50, 16, v225
	v_and_b32_e32 v51, 0xffff0000, v225
	v_pk_mul_f32 v[16:17], v[16:17], v[170:171]
	v_pk_mul_f32 v[18:19], v[18:19], v[50:51]
	s_waitcnt vmcnt(3)
	v_lshlrev_b32_e32 v170, 16, v226
	v_and_b32_e32 v171, 0xffff0000, v226
	v_lshlrev_b32_e32 v50, 16, v227
	v_and_b32_e32 v51, 0xffff0000, v227
	v_pk_mul_f32 v[44:45], v[44:45], v[170:171]
	v_pk_mul_f32 v[46:47], v[46:47], v[50:51]
	v_lshlrev_b32_e32 v170, 16, v228
	v_and_b32_e32 v171, 0xffff0000, v228
	v_lshlrev_b32_e32 v50, 16, v229
	v_and_b32_e32 v51, 0xffff0000, v229
	v_pk_mul_f32 v[40:41], v[40:41], v[170:171]
	v_pk_mul_f32 v[42:43], v[42:43], v[50:51]
	s_waitcnt vmcnt(2)
	v_lshlrev_b32_e32 v170, 16, v230
	v_and_b32_e32 v171, 0xffff0000, v230
	v_lshlrev_b32_e32 v50, 16, v231
	v_and_b32_e32 v51, 0xffff0000, v231
	v_pk_mul_f32 v[12:13], v[12:13], v[170:171]
	v_pk_mul_f32 v[14:15], v[14:15], v[50:51]
	v_lshlrev_b32_e32 v170, 16, v232
	v_and_b32_e32 v171, 0xffff0000, v232
	v_lshlrev_b32_e32 v50, 16, v233
	v_and_b32_e32 v51, 0xffff0000, v233
	v_pk_mul_f32 v[8:9], v[8:9], v[170:171]
	v_pk_mul_f32 v[10:11], v[10:11], v[50:51]
	s_waitcnt vmcnt(1)
	v_lshlrev_b32_e32 v170, 16, v132
	v_and_b32_e32 v171, 0xffff0000, v132
	v_lshlrev_b32_e32 v50, 16, v133
	v_and_b32_e32 v51, 0xffff0000, v133
	v_pk_mul_f32 v[36:37], v[36:37], v[170:171]
	v_pk_mul_f32 v[38:39], v[38:39], v[50:51]
	v_lshlrev_b32_e32 v170, 16, v134
	v_and_b32_e32 v171, 0xffff0000, v134
	v_lshlrev_b32_e32 v50, 16, v135
	v_and_b32_e32 v51, 0xffff0000, v135
	v_pk_mul_f32 v[32:33], v[32:33], v[170:171]
	v_pk_mul_f32 v[34:35], v[34:35], v[50:51]
	s_waitcnt vmcnt(0)
	v_lshlrev_b32_e32 v170, 16, v160
	v_and_b32_e32 v171, 0xffff0000, v160
	v_lshlrev_b32_e32 v50, 16, v161
	v_and_b32_e32 v51, 0xffff0000, v161
	v_pk_mul_f32 v[4:5], v[4:5], v[170:171]
	v_pk_mul_f32 v[6:7], v[6:7], v[50:51]
	v_lshlrev_b32_e32 v170, 16, v162
	v_and_b32_e32 v171, 0xffff0000, v162
	v_lshlrev_b32_e32 v50, 16, v163
	v_and_b32_e32 v51, 0xffff0000, v163
	v_pk_mul_f32 v[0:1], v[0:1], v[170:171]
	v_pk_mul_f32 v[2:3], v[2:3], v[50:51]

;     DI void operator()(const f32x4 (&acc)[2][2][4][2], const pg8::Unit& u, int wr, int wc, int fr, int fq) const {
;     ...
;             for (int m = 0; m < 4; ++m) { const size_t off = (size_t)(row0 + ai * 128 + m * 16) * D + col0;
; #pragma unroll
;                 for (int bj = 0; bj < 2; ++bj)
; #pragma unroll
;                     for (int n = 0; n < 2; ++n) { const f32x4 xv = *(const f32x4*)(xin + off + bj * 128 + n * 16); *(f32x4*)(out + off + bj * 128 + n * 16) = xv + acc[ai][bj][m][n]; }
;                 asm volatile("" ::: "memory"); }
.LBB0_223:
	v_lshl_add_u32 v152, s31, 8, v154
	v_lshl_or_b32 v150, s30, 8, v156
	v_lshlrev_b32_e32 v153, 12, v152
	v_lshl_add_u32 v153, v150, 2, v153
	s_andn2_b64 vcc, exec, s[6:7]
	s_mov_b32 s16, s50
	s_mov_b32 s17, s51
	global_load_dwordx4 v[148:151], v153, s[16:17]
	global_load_dwordx4 v[158:161], v153, s[16:17] offset:64
	global_load_dwordx4 v[162:165], v153, s[16:17] offset:512
	global_load_dwordx4 v[166:169], v153, s[16:17] offset:576
	s_add_u32 s16, s16, 0x10000
	s_addc_u32 s17, s17, 0
	global_load_dwordx4 v[178:181], v153, s[16:17]
	global_load_dwordx4 v[182:185], v153, s[16:17] offset:64
	global_load_dwordx4 v[186:189], v153, s[16:17] offset:512
	global_load_dwordx4 v[190:193], v153, s[16:17] offset:576
	s_add_u32 s16, s16, 0x10000
	s_addc_u32 s17, s17, 0
	global_load_dwordx4 v[194:197], v153, s[16:17]
	global_load_dwordx4 v[198:201], v153, s[16:17] offset:64
	global_load_dwordx4 v[202:205], v153, s[16:17] offset:512
	global_load_dwordx4 v[206:209], v153, s[16:17] offset:576
	s_add_u32 s16, s16, 0x10000
	s_addc_u32 s17, s17, 0
	global_load_dwordx4 v[210:213], v153, s[16:17]
	global_load_dwordx4 v[214:217], v153, s[16:17] offset:64
	global_load_dwordx4 v[218:221], v153, s[16:17] offset:512
	global_load_dwordx4 v[222:225], v153, s[16:17] offset:576
	s_mov_b32 s16, s90
	s_mov_b32 s17, s91
	s_waitcnt vmcnt(15)
	v_pk_add_f32 v[148:149], v[126:127], v[148:149]
	v_pk_add_f32 v[150:151], v[128:129], v[150:151]
	global_store_dwordx4 v153, v[148:151], s[16:17]
	s_waitcnt vmcnt(15)
	v_pk_add_f32 v[158:159], v[122:123], v[158:159]
	v_pk_add_f32 v[160:161], v[124:125], v[160:161]
	global_store_dwordx4 v153, v[158:161], s[16:17] offset:64
	s_waitcnt vmcnt(15)
	v_pk_add_f32 v[162:163], v[118:119], v[162:163]
	v_pk_add_f32 v[164:165], v[120:121], v[164:165]
	global_store_dwordx4 v153, v[162:165], s[16:17] offset:512
	s_waitcnt vmcnt(15)
	v_pk_add_f32 v[166:167], v[114:115], v[166:167]
	v_pk_add_f32 v[168:169], v[116:117], v[168:169]
	global_store_dwordx4 v153, v[166:169], s[16:17] offset:576
	s_add_u32 s16, s16, 0x10000
	s_addc_u32 s17, s17, 0
	s_waitcnt vmcnt(15)
	v_pk_add_f32 v[178:179], v[110:111], v[178:179]
	v_pk_add_f32 v[180:181], v[112:113], v[180:181]
	global_store_dwordx4 v153, v[178:181], s[16:17]
	s_waitcnt vmcnt(15)
	v_pk_add_f32 v[182:183], v[106:107], v[182:183]
	v_pk_add_f32 v[184:185], v[108:109], v[184:185]
	global_store_dwordx4 v153, v[182:185], s[16:17] offset:64
	s_waitcnt vmcnt(15)
	v_pk_add_f32 v[186:187], v[102:103], v[186:187]
	v_pk_add_f32 v[188:189], v[104:105], v[188:189]
	global_store_dwordx4 v153, v[186:189], s[16:17] offset:512
	s_waitcnt vmcnt(15)
	v_pk_add_f32 v[190:191], v[98:99], v[190:191]
	v_pk_add_f32 v[192:193], v[100:101], v[192:193]
	global_store_dwordx4 v153, v[190:193], s[16:17] offset:576
	s_add_u32 s16, s16, 0x10000
	s_addc_u32 s17, s17, 0
	s_waitcnt vmcnt(15)
	v_pk_add_f32 v[194:195], v[94:95], v[194:195]
	v_pk_add_f32 v[196:197], v[96:97], v[196:197]
	global_store_dwordx4 v153, v[194:197], s[16:17]
	s_waitcnt vmcnt(15)
	v_pk_add_f32 v[198:199], v[90:91], v[198:199]
	v_pk_add_f32 v[200:201], v[92:93], v[200:201]
	global_store_dwordx4 v153, v[198:201], s[16:17] offset:64
	s_waitcnt vmcnt(15)
	v_pk_add_f32 v[202:203], v[86:87], v[202:203]
	v_pk_add_f32 v[204:205], v[88:89], v[204:205]
	global_store_dwordx4 v153, v[202:205], s[16:17] offset:512
	s_waitcnt vmcnt(15)
	v_pk_add_f32 v[206:207], v[82:83], v[206:207]
	v_pk_add_f32 v[208:209], v[84:85], v[208:209]
	global_store_dwordx4 v153, v[206:209], s[16:17] offset:576
	s_add_u32 s16, s16, 0x10000
	s_addc_u32 s17, s17, 0
	s_waitcnt vmcnt(15)
	v_pk_add_f32 v[210:211], v[78:79], v[210:211]
	v_pk_add_f32 v[212:213], v[80:81], v[212:213]
	global_store_dwordx4 v153, v[210:213], s[16:17]
	s_waitcnt vmcnt(15)
	v_pk_add_f32 v[214:215], v[74:75], v[214:215]
	v_pk_add_f32 v[216:217], v[76:77], v[216:217]
	global_store_dwordx4 v153, v[214:217], s[16:17] offset:64
	s_waitcnt vmcnt(15)
	v_pk_add_f32 v[218:219], v[70:71], v[218:219]
	v_pk_add_f32 v[220:221], v[72:73], v[220:221]
	global_store_dwordx4 v153, v[218:221], s[16:17] offset:512
	s_waitcnt vmcnt(15)
;     DI void operator()(const f32x4 (&acc)[2][2][4][2], const pg8::Unit& u, int wr, int wc, int fr, int fq) const {
;     ...
;             for (int m = 0; m < 4; ++m) { const size_t off = (size_t)(row0 + ai * 128 + m * 16) * D + col0;
; #pragma unroll
;                 for (int bj = 0; bj < 2; ++bj)
; #pragma unroll
;                     for (int n = 0; n < 2; ++n) { const f32x4 xv = *(const f32x4*)(xin + off + bj * 128 + n * 16); *(f32x4*)(out + off + bj * 128 + n * 16) = xv + acc[ai][bj][m][n]; }
;                 asm volatile("" ::: "memory"); }
	v_pk_add_f32 v[222:223], v[66:67], v[222:223]
	v_pk_add_f32 v[224:225], v[68:69], v[224:225]
	global_store_dwordx4 v153, v[222:225], s[16:17] offset:576
	s_add_u32 s16, s50, 0x80000
	s_addc_u32 s17, s51, 0
	global_load_dwordx4 v[148:151], v153, s[16:17]
	global_load_dwordx4 v[158:161], v153, s[16:17] offset:64
	global_load_dwordx4 v[162:165], v153, s[16:17] offset:512
	global_load_dwordx4 v[166:169], v153, s[16:17] offset:576
	s_add_u32 s16, s16, 0x10000
	s_addc_u32 s17, s17, 0
	global_load_dwordx4 v[178:181], v153, s[16:17]
	global_load_dwordx4 v[182:185], v153, s[16:17] offset:64
	global_load_dwordx4 v[186:189], v153, s[16:17] offset:512
	global_load_dwordx4 v[190:193], v153, s[16:17] offset:576
	s_add_u32 s16, s16, 0x10000
	s_addc_u32 s17, s17, 0
	global_load_dwordx4 v[194:197], v153, s[16:17]
	global_load_dwordx4 v[198:201], v153, s[16:17] offset:64
	global_load_dwordx4 v[202:205], v153, s[16:17] offset:512
	global_load_dwordx4 v[206:209], v153, s[16:17] offset:576
	s_add_u32 s16, s16, 0x10000
	s_addc_u32 s17, s17, 0
	global_load_dwordx4 v[210:213], v153, s[16:17]
	global_load_dwordx4 v[214:217], v153, s[16:17] offset:64
	global_load_dwordx4 v[218:221], v153, s[16:17] offset:512
	global_load_dwordx4 v[222:225], v153, s[16:17] offset:576
	s_add_u32 s16, s90, 0x80000
	s_addc_u32 s17, s91, 0
	s_waitcnt vmcnt(15)
	v_pk_add_f32 v[148:149], v[62:63], v[148:149]
	v_pk_add_f32 v[150:151], v[64:65], v[150:151]
	global_store_dwordx4 v153, v[148:151], s[16:17]
	s_waitcnt vmcnt(15)
	v_pk_add_f32 v[158:159], v[58:59], v[158:159]
	v_pk_add_f32 v[160:161], v[60:61], v[160:161]
	global_store_dwordx4 v153, v[158:161], s[16:17] offset:64
	s_waitcnt vmcnt(15)
	v_pk_add_f32 v[162:163], v[54:55], v[162:163]
	v_pk_add_f32 v[164:165], v[56:57], v[164:165]
	global_store_dwordx4 v153, v[162:165], s[16:17] offset:512
	s_waitcnt vmcnt(15)
	v_pk_add_f32 v[166:167], v[50:51], v[166:167]
	v_pk_add_f32 v[168:169], v[52:53], v[168:169]
	global_store_dwordx4 v153, v[166:169], s[16:17] offset:576
	s_add_u32 s16, s16, 0x10000
	s_addc_u32 s17, s17, 0
	s_waitcnt vmcnt(15)
	v_pk_add_f32 v[178:179], v[44:45], v[178:179]
	v_pk_add_f32 v[180:181], v[46:47], v[180:181]
	global_store_dwordx4 v153, v[178:181], s[16:17]
	s_waitcnt vmcnt(15)
	v_pk_add_f32 v[182:183], v[40:41], v[182:183]
	v_pk_add_f32 v[184:185], v[42:43], v[184:185]
	global_store_dwordx4 v153, v[182:185], s[16:17] offset:64
	s_waitcnt vmcnt(15)
	v_pk_add_f32 v[186:187], v[36:37], v[186:187]
	v_pk_add_f32 v[188:189], v[38:39], v[188:189]
	global_store_dwordx4 v153, v[186:189], s[16:17] offset:512
	s_waitcnt vmcnt(15)
	v_pk_add_f32 v[190:191], v[32:33], v[190:191]
	v_pk_add_f32 v[192:193], v[34:35], v[192:193]
	global_store_dwordx4 v153, v[190:193], s[16:17] offset:576
	s_add_u32 s16, s16, 0x10000
	s_addc_u32 s17, s17, 0
	s_waitcnt vmcnt(15)
	v_pk_add_f32 v[194:195], v[28:29], v[194:195]
	v_pk_add_f32 v[196:197], v[30:31], v[196:197]
	global_store_dwordx4 v153, v[194:197], s[16:17]
	s_waitcnt vmcnt(15)
	v_pk_add_f32 v[198:199], v[24:25], v[198:199]
	v_pk_add_f32 v[200:201], v[26:27], v[200:201]
	global_store_dwordx4 v153, v[198:201], s[16:17] offset:64
	s_waitcnt vmcnt(15)
	v_pk_add_f32 v[202:203], v[20:21], v[202:203]
	v_pk_add_f32 v[204:205], v[22:23], v[204:205]
	global_store_dwordx4 v153, v[202:205], s[16:17] offset:512
	s_waitcnt vmcnt(15)
	v_pk_add_f32 v[206:207], v[16:17], v[206:207]
	v_pk_add_f32 v[208:209], v[18:19], v[208:209]
	global_store_dwordx4 v153, v[206:209], s[16:17] offset:576
	s_add_u32 s16, s16, 0x10000
	s_addc_u32 s17, s17, 0
	s_waitcnt vmcnt(15)
	v_pk_add_f32 v[210:211], v[12:13], v[210:211]
	v_pk_add_f32 v[212:213], v[14:15], v[212:213]
	global_store_dwordx4 v153, v[210:213], s[16:17]
	s_waitcnt vmcnt(15)
	v_pk_add_f32 v[214:215], v[8:9], v[214:215]
	v_pk_add_f32 v[216:217], v[10:11], v[216:217]
	global_store_dwordx4 v153, v[214:217], s[16:17] offset:64
	s_waitcnt vmcnt(15)
	v_pk_add_f32 v[218:219], v[4:5], v[218:219]
	v_pk_add_f32 v[220:221], v[6:7], v[220:221]
	global_store_dwordx4 v153, v[218:221], s[16:17] offset:512
	s_waitcnt vmcnt(15)
	v_pk_add_f32 v[222:223], v[0:1], v[222:223]
	v_pk_add_f32 v[224:225], v[2:3], v[224:225]
	global_store_dwordx4 v153, v[222:225], s[16:17] offset:576
	s_mov_b64 s[16:17], -1
	s_cbranch_vccnz .LBB0_212
	s_andn2_b64 vcc, exec, s[0:1]
	s_cbranch_vccnz .LBB0_211
	s_barrier
	s_branch .LBB0_211
